# cross-attention: waves 4-7 delayed once (s_sleep 40) before the q-tile loop so SIMD partners run staggered
# baseline (speedup 1.0000x reference)
; __device__ __forceinline__ void cross_unit(lbyte* lds, bf16* CQ, const bf16* CKV, const float* gq, const float* gk, int layer, int b, int hc, int qblk0, int qstep, int nq) {
;     ...
;     __syncthreads();
; #pragma unroll 1
;     for (int qi = 0; qi < nq; ++qi) { const int qblk = qblk0 + qi * qstep;
;     const size_t row = (size_t)b * SEQ + qblk * 256 + 32 * wid + l31;
;     bf16* qrow = CQ + row * 512 + hc * 128;
;     s16x8 qf[8];
; #pragma unroll
;     for (int c = 0; c < 8; ++c) qf[c] = *(const s16x8*)(qrow + 16 * c + 8 * h);
.LBB0_985:
	s_or_b64 exec, exec, s[0:1]
	v_readlane_b32 s0, v255, 8
	v_readlane_b32 s1, v255, 9
	s_andn2_b64 vcc, exec, s[0:1]
	s_waitcnt vmcnt(0) lgkmcnt(0)
	s_barrier
	s_cbranch_vccnz .LBB0_993
	s_add_u32 s6, s5, 0x1ac00000
	s_addc_u32 s7, s4, 0
	s_lshl_b64 s[0:1], s[86:87], 2
	s_add_u32 s0, s9, s0
	s_addc_u32 s1, s8, s1
	s_ashr_i32 s4, s10, 1
	v_readlane_b32 s8, v254, 14
	v_and_b32_e32 v4, 31, v5
	s_andn2_b32 s4, s4, 31
	v_readlane_b32 s9, v254, 15
	s_ashr_i32 s5, s4, 31
	v_or_b32_e32 v2, s8, v4
	v_mov_b32_e32 v3, s9
	v_lshl_add_u64 v[148:149], v[2:3], 0, s[4:5]
	v_readlane_b32 s4, v254, 16
	v_readlane_b32 s5, v254, 17
	v_bfe_u32 v5, v5, 5, 1
	s_lshl_b64 s[4:5], s[4:5], 1
	s_add_u32 s4, s6, s4
	v_lshlrev_b32_e32 v0, 5, v5
	s_addc_u32 s5, s7, s5
	v_lshl_add_u64 v[150:151], s[0:1], 0, v[0:1]
	v_lshlrev_b32_e32 v0, 4, v5
	v_mul_u32_u24_e32 v2, 0x210, v4
	v_lshl_add_u64 v[152:153], s[4:5], 0, v[0:1]
	v_lshl_or_b32 v156, v5, 3, v2
	v_mad_u32_u24 v157, v4, s29, v0
	v_readfirstlane_b32 s0, v232
	s_nop 0
	s_lshr_b32 s0, s0, 6
	s_cmp_ge_u32 s0, 4
	s_cbranch_scc0 .Lcx_stag_done
	s_sleep 40
.Lcx_stag_done:
	s_mov_b32 s0, 0
	s_branch .LBB0_988
